# select_row: when >=256 keys are >= 1.0, an upward binade scan (2,4,8,16) replaces the generic bit-31 search, then the packed 7-bit digit phase and bits 15..0; same threshold and selection
# speedup vs baseline: 1.0057x; 1.0042x over previous
; DI void select_row(const float* SC, unsigned* dmask, int b, int t, int lane) {
;     ...
;     unsigned T = 0u; bool hit = false; int startbit = 31;
;     {
;         int cnt; SEL_COUNT(0xBF800000u, cnt);
;         if (cnt < 256) {
; #pragma unroll 1
;             for (unsigned e = 0x7Eu; e >= 0x7Au; --e) {
;                 const unsigned cand = 0x80000000u | (e << 23); SEL_COUNT(cand, cnt);
;                 if (cnt >= 256) { T = cand; startbit = 22; hit = (cnt == 256); break; }
;             }
;         }
;     }
.Lsel_up:
	s_mov_b32 s14, s62
	s_mov_b32 s80, 4
.Lsel_up_loop:
	s_add_u32 s66, s14, 0x800000
	v_mov_b32_e32 v4, 0
	v_cmp_le_u32_e32 vcc, s66, v11
	v_addc_co_u32_e32 v4, vcc, 0, v4, vcc
	v_cmp_le_u32_e32 vcc, s66, v10
	v_addc_co_u32_e32 v4, vcc, 0, v4, vcc
	v_cmp_le_u32_e32 vcc, s66, v121
	v_addc_co_u32_e32 v4, vcc, 0, v4, vcc
	v_cmp_le_u32_e32 vcc, s66, v9
	v_addc_co_u32_e32 v4, vcc, 0, v4, vcc
	v_cmp_le_u32_e32 vcc, s66, v7
	v_addc_co_u32_e32 v4, vcc, 0, v4, vcc
	v_cmp_le_u32_e32 vcc, s66, v6
	v_addc_co_u32_e32 v4, vcc, 0, v4, vcc
	v_cmp_le_u32_e32 vcc, s66, v8
	v_addc_co_u32_e32 v4, vcc, 0, v4, vcc
	v_cmp_le_u32_e32 vcc, s66, v5
	v_addc_co_u32_e32 v4, vcc, 0, v4, vcc
	s_and_b64 vcc, exec, s[82:83]
	s_cbranch_vccnz .Lsel_up_g1
	v_cmp_le_u32_e32 vcc, s66, v33
	v_addc_co_u32_e32 v4, vcc, 0, v4, vcc
	v_cmp_le_u32_e32 vcc, s66, v41
	v_addc_co_u32_e32 v4, vcc, 0, v4, vcc
	v_cmp_le_u32_e32 vcc, s66, v32
	v_addc_co_u32_e32 v4, vcc, 0, v4, vcc
	v_cmp_le_u32_e32 vcc, s66, v42
	v_addc_co_u32_e32 v4, vcc, 0, v4, vcc
	v_cmp_le_u32_e32 vcc, s66, v29
	v_addc_co_u32_e32 v4, vcc, 0, v4, vcc
	v_cmp_le_u32_e32 vcc, s66, v30
	v_addc_co_u32_e32 v4, vcc, 0, v4, vcc
	v_cmp_le_u32_e32 vcc, s66, v28
	v_addc_co_u32_e32 v4, vcc, 0, v4, vcc
	v_cmp_le_u32_e32 vcc, s66, v31
	v_addc_co_u32_e32 v4, vcc, 0, v4, vcc
.Lsel_up_g1:
	s_and_b64 vcc, exec, s[78:79]
	s_cbranch_vccnz .Lsel_up_g2
	v_cmp_le_u32_e32 vcc, s66, v24
	v_addc_co_u32_e32 v4, vcc, 0, v4, vcc
	v_cmp_le_u32_e32 vcc, s66, v25
	v_addc_co_u32_e32 v4, vcc, 0, v4, vcc
	v_cmp_le_u32_e32 vcc, s66, v26
	v_addc_co_u32_e32 v4, vcc, 0, v4, vcc
	v_cmp_le_u32_e32 vcc, s66, v27
	v_addc_co_u32_e32 v4, vcc, 0, v4, vcc
	v_cmp_le_u32_e32 vcc, s66, v21
	v_addc_co_u32_e32 v4, vcc, 0, v4, vcc
	v_cmp_le_u32_e32 vcc, s66, v22
	v_addc_co_u32_e32 v4, vcc, 0, v4, vcc
	v_cmp_le_u32_e32 vcc, s66, v18
	v_addc_co_u32_e32 v4, vcc, 0, v4, vcc
	v_cmp_le_u32_e32 vcc, s66, v23
	v_addc_co_u32_e32 v4, vcc, 0, v4, vcc
.Lsel_up_g2:
	s_and_b64 vcc, exec, s[76:77]
	s_cbranch_vccnz .Lsel_up_g3
	v_cmp_le_u32_e32 vcc, s66, v15
	v_addc_co_u32_e32 v4, vcc, 0, v4, vcc
	v_cmp_le_u32_e32 vcc, s66, v16
	v_addc_co_u32_e32 v4, vcc, 0, v4, vcc
	v_cmp_le_u32_e32 vcc, s66, v19
	v_addc_co_u32_e32 v4, vcc, 0, v4, vcc
	v_cmp_le_u32_e32 vcc, s66, v20
	v_addc_co_u32_e32 v4, vcc, 0, v4, vcc
	v_cmp_le_u32_e32 vcc, s66, v13
	v_addc_co_u32_e32 v4, vcc, 0, v4, vcc
	v_cmp_le_u32_e32 vcc, s66, v14
	v_addc_co_u32_e32 v4, vcc, 0, v4, vcc
	v_cmp_le_u32_e32 vcc, s66, v12
	v_addc_co_u32_e32 v4, vcc, 0, v4, vcc
	v_cmp_le_u32_e32 vcc, s66, v17
	v_addc_co_u32_e32 v4, vcc, 0, v4, vcc
.Lsel_up_g3:
	s_nop 1
	v_add_u32_dpp v4, v4, v4 row_shr:1 row_mask:0xf bank_mask:0xf bound_ctrl:1
	s_nop 1
	v_add_u32_dpp v4, v4, v4 row_shr:2 row_mask:0xf bank_mask:0xf bound_ctrl:1
	s_nop 1
	v_add_u32_dpp v4, v4, v4 row_shr:4 row_mask:0xf bank_mask:0xf bound_ctrl:1
	s_nop 1
	v_add_u32_dpp v4, v4, v4 row_shr:8 row_mask:0xf bank_mask:0xf bound_ctrl:1
	s_nop 1
	v_add_u32_dpp v4, v4, v4 row_bcast:15 row_mask:0xa bank_mask:0xf
	s_nop 1
	v_add_u32_dpp v4, v4, v4 row_bcast:31 row_mask:0xc bank_mask:0xf
	s_nop 1
	v_readlane_b32 s10, v4, 63
	s_cmpk_lt_i32 s10, 0x100
	s_cbranch_scc1 .Lsel7
	s_mov_b32 s14, s66
	s_cmpk_eq_i32 s10, 0x100
	s_cbranch_scc1 .Lsel_up_hit
	s_add_i32 s80, s80, -1
	s_cmp_lg_u32 s80, 0
	s_cbranch_scc1 .Lsel_up_loop
	s_branch .LBB0_570
.Lsel_up_hit:
	v_mov_b32_e32 v2, s14
	s_mov_b64 s[8:9], -1
	s_branch .LBB0_582
